# MLA tile loop: next tile's global loads and their address VALU issued inside the QK MFMA block (MFMA shadow) instead of in front of it; on top of v56
# baseline (speedup 1.0000x reference)
; #define LAS __attribute__((address_space(3)))
; template <int MODE, int NQ> ...
;     ...
;         if (MODE == M_SEL) { jn = rem ? (int)__builtin_ctzll(rem) : -1; rem &= rem - 1ull; } else { jn = (j + 1 <= jhi) ? j + 1 : -1; }
;         if (jn >= 0) stage_load<HASP, HASV>(st, Kg + (size_t)jn * 64 * ldk, ldk, Pg + (size_t)jn * 64 * 64, Vg + (size_t)jn * 64 * ldv, ldv, tid);
;         const bool lvw = (MODE == M_SEL) ? (((mymask >> j) & 1ull) != 0ull) : true;
;         if (!((MODE == M_MLA && 64 * j > wmax) || (MODE == M_SEL && !__any(lvw)))) {
;             const LAS unsigned char* kb = kb_l + bsel * KBUF; const LAS unsigned char* vb = vb_l + bsel * VBUF;
;             f32x16 s0, s1;
; #pragma unroll
;             for (int r = 0; r < 16; ++r) { s0[r] = 0.f; s1[r] = 0.f; }
;             {
;                 constexpr int KW = (NQ == 8) ? 6 : ATT_KW12;
;                 bf16x8 kf[KW];
; #pragma unroll
;                 for (int i = 0; i < KW; ++i) kf[i] = *(const LAS bf16x8*)(kb + (i & 1) * 32 * KP + (i >> 1) * 32);
;                 __builtin_amdgcn_sched_barrier(0);
; #pragma unroll
;                 for (int i = 0; i < 2 * NQ; ++i) {
;                     if (i & 1) s1 = __builtin_amdgcn_mfma_f32_32x32x16_bf16(kf[i % KW], qf[i >> 1], s1, 0, 0, 0);
;                     else s0 = __builtin_amdgcn_mfma_f32_32x32x16_bf16(kf[i % KW], qf[i >> 1], s0, 0, 0, 0);
;                     if (i + KW < 2 * NQ) { kf[i % KW] = *(const LAS bf16x8*)(kb + ((i + KW) & 1) * 32 * KP + ((i + KW) >> 1) * 32); __builtin_amdgcn_sched_barrier(0); }
;                 }
.LBB0_964:
	s_cmp_gt_i32 s33, s96
	s_cbranch_scc1 .Lmla_skip_ld
	v_add_u32_e32 v189, s0, v171
	ds_read_b128 v[66:69], v189
	ds_read_b128 v[192:195], v189 offset:32
	ds_read_b128 v[82:85], v189 offset:12800
	ds_read_b128 v[196:199], v189 offset:12832
	ds_read_b128 v[200:203], v189 offset:64
	ds_read_b128 v[204:207], v189 offset:96
	ds_read_b128 v[208:211], v189 offset:12864
	ds_read_b128 v[212:215], v189 offset:12896
	ds_read_b128 v[216:219], v189 offset:128
	ds_read_b128 v[220:223], v189 offset:160
	ds_read_b128 v[224:227], v189 offset:12928
	ds_read_b128 v[228:231], v189 offset:12960
	s_waitcnt lgkmcnt(11)
	v_mfma_f32_32x32x16_bf16 v[66:81], v[66:69], v[98:101], 0
	ds_read_b128 v[232:235], v189 offset:192
	s_waitcnt lgkmcnt(10)
	v_mfma_f32_32x32x16_bf16 v[82:97], v[82:85], v[98:101], 0
	s_cmp_eq_u32 s98, 0
	s_cbranch_scc1 .Lmla_nold
	v_lshl_add_u64 v[246:247], s[30:31], 0, v[180:181]
	v_add_co_u32_e32 v248, vcc, 0x34840000, v246
	s_nop 1
	v_addc_co_u32_e32 v249, vcc, 0, v247, vcc
	v_add_co_u32_e32 v250, vcc, 0x34860000, v246
	s_nop 1
	v_addc_co_u32_e32 v251, vcc, 0, v247, vcc
	global_load_dwordx4 v[146:149], v[248:249], off
	global_load_dwordx4 v[150:153], v[250:251], off
	v_add_co_u32_e32 v250, vcc, 0x38840000, v246
	v_lshl_add_u64 v[248:249], s[30:31], 0, v[178:179]
	s_nop 0
	v_addc_co_u32_e32 v251, vcc, 0, v247, vcc
	v_add_co_u32_e32 v246, vcc, 0x38860000, v246
	global_load_dwordx4 v[154:157], v[248:249], off
	global_load_dwordx4 v[158:161], v[250:251], off
	v_addc_co_u32_e32 v247, vcc, 0, v247, vcc
	global_load_dwordx4 v[162:165], v[246:247], off
; #define LAS __attribute__((address_space(3)))
; template <int MODE, int NQ> ...
;     ...
;                 for (int i = 0; i < KW; ++i) kf[i] = *(const LAS bf16x8*)(kb + (i & 1) * 32 * KP + (i >> 1) * 32);
;                 __builtin_amdgcn_sched_barrier(0);
; #pragma unroll
;                 for (int i = 0; i < 2 * NQ; ++i) {
;                     if (i & 1) s1 = __builtin_amdgcn_mfma_f32_32x32x16_bf16(kf[i % KW], qf[i >> 1], s1, 0, 0, 0);
;                     else s0 = __builtin_amdgcn_mfma_f32_32x32x16_bf16(kf[i % KW], qf[i >> 1], s0, 0, 0, 0);
;                     if (i + KW < 2 * NQ) { kf[i % KW] = *(const LAS bf16x8*)(kb + ((i + KW) & 1) * 32 * KP + ((i + KW) >> 1) * 32); __builtin_amdgcn_sched_barrier(0); }
;                 }
;             }
;             const int hl = hiB - 64 * j - 4 * hi, ll = loB - 64 * j - 4 * hi;
;             const bool lv = lvw;
;             bool need = true;
;             if (MODE == M_WIN || MODE == M_MLA || MODE == M_SEL) need = __any(!((hl >= 63) && (ll < 0)));
;             if (need) {
;                 const float NEG = -__builtin_inff();
; #pragma unroll
;                 for (int r = 0; r < 16; ++r) { const int c = (r & 3) + 8 * (r >> 2);
;                     if (!(lv && c <= hl && c > ll)) s0[r] = NEG;
;                     if (!(lv && c + 32 <= hl && c + 32 > ll)) s1[r] = NEG; }
.Lmla_nold:
	ds_read_b128 v[236:239], v189 offset:12992
	v_mfma_f32_32x32x16_bf16 v[66:81], v[192:195], v[102:105], v[66:81]
	ds_read_b128 v[240:243], v189 offset:224
	s_waitcnt lgkmcnt(11)
	v_mfma_f32_32x32x16_bf16 v[82:97], v[196:199], v[102:105], v[82:97]
	ds_read_b128 v[192:195], v189 offset:13024
	s_waitcnt lgkmcnt(11)
	v_mfma_f32_32x32x16_bf16 v[66:81], v[200:203], v[106:109], v[66:81]
	ds_read_b128 v[196:199], v189 offset:256
	s_waitcnt lgkmcnt(10)
	v_mfma_f32_32x32x16_bf16 v[82:97], v[208:211], v[106:109], v[82:97]
	ds_read_b128 v[200:203], v189 offset:13056
	v_mfma_f32_32x32x16_bf16 v[66:81], v[204:207], v[110:113], v[66:81]
	ds_read_b128 v[208:211], v189 offset:288
	s_waitcnt lgkmcnt(11)
	v_mfma_f32_32x32x16_bf16 v[82:97], v[212:215], v[110:113], v[82:97]
	ds_read_b128 v[204:207], v189 offset:13088
	s_waitcnt lgkmcnt(11)
	v_mfma_f32_32x32x16_bf16 v[66:81], v[216:219], v[114:117], v[66:81]
	ds_read_b128 v[212:215], v189 offset:320
	s_waitcnt lgkmcnt(10)
	v_mfma_f32_32x32x16_bf16 v[82:97], v[224:227], v[114:117], v[82:97]
	ds_read_b128 v[216:219], v189 offset:13120
	v_mfma_f32_32x32x16_bf16 v[66:81], v[220:223], v[118:121], v[66:81]
	ds_read_b128 v[224:227], v189 offset:352
	s_waitcnt lgkmcnt(11)
	v_mfma_f32_32x32x16_bf16 v[82:97], v[228:231], v[118:121], v[82:97]
	ds_read_b128 v[220:223], v189 offset:13152
	s_waitcnt lgkmcnt(11)
	v_mfma_f32_32x32x16_bf16 v[66:81], v[232:235], v[122:125], v[66:81]
	v_cmp_gt_i32_e32 vcc, 63, v187
	s_waitcnt lgkmcnt(10)
	v_mfma_f32_32x32x16_bf16 v[82:97], v[236:239], v[122:125], v[82:97]
	s_waitcnt lgkmcnt(9)
	v_mfma_f32_32x32x16_bf16 v[66:81], v[240:243], v[126:129], v[66:81]
	s_waitcnt lgkmcnt(8)
	v_mfma_f32_32x32x16_bf16 v[82:97], v[192:195], v[126:129], v[82:97]
	s_waitcnt lgkmcnt(7)
	v_mfma_f32_32x32x16_bf16 v[66:81], v[196:199], v[130:133], v[66:81]
	s_waitcnt lgkmcnt(6)
	v_mfma_f32_32x32x16_bf16 v[82:97], v[200:203], v[130:133], v[82:97]
	s_waitcnt lgkmcnt(5)
	v_mfma_f32_32x32x16_bf16 v[66:81], v[208:211], v[134:137], v[66:81]
	s_waitcnt lgkmcnt(4)
	v_mfma_f32_32x32x16_bf16 v[82:97], v[204:207], v[134:137], v[82:97]
	s_waitcnt lgkmcnt(3)
	v_mfma_f32_32x32x16_bf16 v[66:81], v[212:215], v[138:141], v[66:81]
	s_waitcnt lgkmcnt(2)
	v_mfma_f32_32x32x16_bf16 v[82:97], v[216:219], v[138:141], v[82:97]
	s_waitcnt lgkmcnt(1)
	v_mfma_f32_32x32x16_bf16 v[66:81], v[224:227], v[142:145], v[66:81]
	s_waitcnt lgkmcnt(0)
	v_mfma_f32_32x32x16_bf16 v[82:97], v[220:223], v[142:145], v[82:97]
	s_cbranch_vccz .LBB0_967
	v_cmp_gt_i32_e64 s[60:61], 26, v187
	v_cmp_gt_i32_e64 s[62:63], 27, v187
	v_cmp_gt_i32_e64 s[58:59], 25, v187
	s_and_b64 s[60:61], s[62:63], s[60:61]
	v_cmp_gt_i32_e64 s[56:57], 24, v187
	s_and_b64 s[58:59], s[60:61], s[58:59]
	v_cmp_gt_i32_e64 s[54:55], 19, v187
	s_and_b64 s[56:57], s[58:59], s[56:57]
	v_cmp_gt_i32_e64 s[52:53], 18, v187
	s_and_b64 s[54:55], s[56:57], s[54:55]
	v_cmp_gt_i32_e64 s[50:51], 17, v187
	s_and_b64 s[52:53], s[54:55], s[52:53]
	v_cmp_gt_i32_e64 s[48:49], 16, v187
	s_and_b64 s[50:51], s[52:53], s[50:51]
	v_cmp_gt_i32_e64 s[46:47], 11, v187
	s_and_b64 s[48:49], s[50:51], s[48:49]
	v_cmp_gt_i32_e64 s[44:45], 10, v187
	s_and_b64 s[46:47], s[48:49], s[46:47]
	v_cmp_gt_i32_e64 s[42:43], 9, v187
	s_and_b64 s[44:45], s[46:47], s[44:45]
	v_cmp_gt_i32_e64 s[40:41], 8, v187
	s_and_b64 s[42:43], s[44:45], s[42:43]
	v_cmp_gt_i32_e64 s[38:39], 3, v187
	s_and_b64 s[40:41], s[42:43], s[40:41]
	v_cmp_gt_i32_e64 s[36:37], 2, v187
	s_and_b64 s[38:39], s[40:41], s[38:39]
	v_cmp_gt_i32_e64 s[34:35], 1, v187
	s_and_b64 s[36:37], s[38:39], s[36:37]
	v_cmp_gt_i32_e64 s[28:29], 0, v187
	s_and_b64 s[34:35], s[36:37], s[34:35]
	s_and_b64 s[28:29], s[34:35], s[28:29]
	v_cmp_gt_i32_e64 s[26:27], 58, v187
	v_cndmask_b32_e64 v66, v66, v1, s[28:29]
	v_cmp_gt_i32_e64 s[28:29], 59, v187
	v_cmp_gt_i32_e64 s[24:25], 57, v187
	s_and_b64 s[26:27], s[28:29], s[26:27]
	v_cmp_gt_i32_e64 s[22:23], 56, v187
	s_and_b64 s[24:25], s[26:27], s[24:25]
	v_cmp_gt_i32_e64 s[20:21], 51, v187
	s_and_b64 s[22:23], s[24:25], s[22:23]
	v_cmp_gt_i32_e64 s[18:19], 50, v187
	s_and_b64 s[20:21], s[22:23], s[20:21]
	v_cmp_gt_i32_e64 s[0:1], 49, v187
	s_and_b64 s[18:19], s[20:21], s[18:19]
	v_cmp_gt_i32_e64 s[16:17], 48, v187
	s_and_b64 s[0:1], s[18:19], s[0:1]
	v_cmp_gt_i32_e64 s[14:15], 43, v187
	v_cndmask_b32_e64 v91, v91, v1, s[0:1]
	s_and_b64 s[0:1], s[0:1], s[16:17]
	v_cmp_gt_i32_e64 s[12:13], 42, v187
	v_cndmask_b32_e64 v90, v90, v1, s[0:1]
	s_and_b64 s[0:1], s[0:1], s[14:15]
	v_cmp_gt_i32_e64 s[10:11], 41, v187
	v_cndmask_b32_e64 v89, v89, v1, s[0:1]
	s_and_b64 s[0:1], s[0:1], s[12:13]
	v_cmp_gt_i32_e64 s[8:9], 40, v187
	v_cndmask_b32_e64 v88, v88, v1, s[0:1]
	s_and_b64 s[0:1], s[0:1], s[10:11]
	v_cmp_gt_i32_e64 s[6:7], 35, v187
	v_cndmask_b32_e64 v87, v87, v1, s[0:1]
	s_and_b64 s[0:1], s[0:1], s[8:9]
	v_cmp_gt_i32_e64 s[4:5], 34, v187
	v_cndmask_b32_e64 v86, v86, v1, s[0:1]
	s_and_b64 s[0:1], s[0:1], s[6:7]
	v_cmp_gt_i32_e64 s[2:3], 33, v187
	v_cndmask_b32_e64 v85, v85, v1, s[0:1]
	s_and_b64 s[0:1], s[0:1], s[4:5]
	v_cmp_gt_i32_e32 vcc, 32, v187
	v_cndmask_b32_e64 v84, v84, v1, s[0:1]
	s_and_b64 s[0:1], s[0:1], s[2:3]
	s_and_b64 vcc, s[0:1], vcc
	v_cndmask_b32_e64 v81, v81, v1, s[62:63]
	v_cndmask_b32_e64 v80, v80, v1, s[60:61]
	v_cndmask_b32_e64 v79, v79, v1, s[58:59]
	v_cndmask_b32_e64 v78, v78, v1, s[56:57]
	v_cndmask_b32_e64 v77, v77, v1, s[54:55]
	v_cndmask_b32_e64 v76, v76, v1, s[52:53]
	v_cndmask_b32_e64 v75, v75, v1, s[50:51]
	v_cndmask_b32_e64 v74, v74, v1, s[48:49]
	v_cndmask_b32_e64 v73, v73, v1, s[46:47]
	v_cndmask_b32_e64 v72, v72, v1, s[44:45]
	v_cndmask_b32_e64 v71, v71, v1, s[42:43]
	v_cndmask_b32_e64 v70, v70, v1, s[40:41]
	v_cndmask_b32_e64 v69, v69, v1, s[38:39]
	v_cndmask_b32_e64 v68, v68, v1, s[36:37]
	v_cndmask_b32_e64 v67, v67, v1, s[34:35]
	v_cndmask_b32_e64 v97, v97, v1, s[28:29]
	v_cndmask_b32_e64 v96, v96, v1, s[26:27]
	v_cndmask_b32_e64 v95, v95, v1, s[24:25]
	v_cndmask_b32_e64 v94, v94, v1, s[22:23]
	v_cndmask_b32_e64 v93, v93, v1, s[20:21]
	v_cndmask_b32_e64 v92, v92, v1, s[18:19]
	v_cndmask_b32_e64 v83, v83, v1, s[0:1]
	v_cndmask_b32_e32 v82, v82, v1, vcc

; template <int MODE, int NQ> ...
;     ...
;     if (j >= 0) stage_load<HASP, HASV>(st, Kg + (size_t)j * 64 * ldk, ldk, Pg + (size_t)j * 64 * 64, Vg + (size_t)j * 64 * ldv, ldv, tid);
;     int it = 0;
;     while (j >= 0) {
;         const int bsel = it & 1;
;         stage_store<HASP, HASV>(st, lds + OFF_K + bsel * KBUF, lds + OFF_V + bsel * VBUF, tid);
;         __syncthreads();
;         int jn;
;         if (MODE == M_SEL) { jn = rem ? (int)__builtin_ctzll(rem) : -1; rem &= rem - 1ull; } else { jn = (j + 1 <= jhi) ? j + 1 : -1; }
;         if (jn >= 0) stage_load<HASP, HASV>(st, Kg + (size_t)jn * 64 * ldk, ldk, Pg + (size_t)jn * 64 * 64, Vg + (size_t)jn * 64 * ldv, ldv, tid);
;         const bool lvw = (MODE == M_SEL) ? (((mymask >> j) & 1ull) != 0ull) : true;
;         if (!((MODE == M_MLA && 64 * j > wmax) || (MODE == M_SEL && !__any(lvw)))) {
.Lmla_skip_ld:
	s_cmp_eq_u32 s98, 0
	s_cbranch_scc1 .LBB0_970
	v_lshl_add_u64 v[246:247], s[30:31], 0, v[180:181]
	v_add_co_u32_e32 v248, vcc, 0x34840000, v246
	s_nop 1
	v_addc_co_u32_e32 v249, vcc, 0, v247, vcc
	v_add_co_u32_e32 v250, vcc, 0x34860000, v246
	s_nop 1
	v_addc_co_u32_e32 v251, vcc, 0, v247, vcc
	global_load_dwordx4 v[146:149], v[248:249], off
	global_load_dwordx4 v[150:153], v[250:251], off
	v_add_co_u32_e32 v250, vcc, 0x38840000, v246
	v_lshl_add_u64 v[248:249], s[30:31], 0, v[178:179]
	s_nop 0
	v_addc_co_u32_e32 v251, vcc, 0, v247, vcc
	v_add_co_u32_e32 v246, vcc, 0x38860000, v246
	global_load_dwordx4 v[154:157], v[248:249], off
	global_load_dwordx4 v[158:161], v[250:251], off
	v_addc_co_u32_e32 v247, vcc, 0, v247, vcc
	global_load_dwordx4 v[162:165], v[246:247], off
	s_branch .LBB0_970
